# v10 with QK MFMA cluster at priority 2 and PV at 1
# speedup vs baseline: 1.0056x; 1.0016x over previous
; #define SBAR() __builtin_amdgcn_sched_barrier(0)
; template <int DQK, int MODE, bool PIPE>
; DI void attn_core(const u16* __restrict__ Qg, const u16* __restrict__ Kg, const u16* __restrict__ Vtg, int ntiles,
;                   int kr_lo, int rs, int r_q, int c_q, int cs, const float* biasL, char* lds, f32x16 (&o)[4], float& l_out, int tid) {
;     ...
;   auto qk = [&](int t, f32x16& p0, f32x16& p1) {
;     const char* kb = lds + (t & 1) * A_BUF + r32 * KSTR + h * 16;
;     if (MODE != 0) {
; #pragma unroll
;       for (int i = 0; i < 16; ++i) { p0[i] = 0.f; p1[i] = 0.f; }
;     }
;     if (MODE == 0) {
;       constexpr int R = 4, NF = 2 * NKS;
;       const unsigned kaddr = (unsigned)(size_t)kb;
;       bf16x8 f[R];
;       SBAR();
;       f[0] = lds_rd128<0>(kaddr); f[1] = lds_rd128<32 * KSTR>(kaddr); f[2] = lds_rd128<32>(kaddr); f[3] = lds_rd128<32 * KSTR + 32>(kaddr);
;       SBAR();
;       __builtin_amdgcn_s_setprio(1);
;       QkStep<DQK, 0, NF, R>::run(kaddr, f, qf, p0, p1, negm);
;       __builtin_amdgcn_s_setprio(0);
;     ...
;     asm volatile("s_nop 7\n\ts_nop 7\n\ts_nop 7" ::: "memory");
;     if (!NEGM && __any(m != 0.f)) {
; #pragma unroll
;       for (int i = 0; i < 16; ++i) {
;         asm("v_sub_f32 %0, %1, %2" : "=v"(p0[i]) : "v"(p0[i]), "v"(m));
;         asm("v_sub_f32 %0, %1, %2" : "=v"(p1[i]) : "v"(p1[i]), "v"(m));
;       }
;     }
.LBB0_821:
	s_bitcmp1_b32 s6, 0
	s_cselect_b32 s7, 0xa800, 0
	s_add_i32 s19, s7, 0
	v_add3_u32 v244, s19, v225, v0
	ds_read_b128 v[66:69], v244 offset:0
	ds_read_b128 v[82:85], v244 offset:0x3200
	ds_read_b128 v[228:231], v244 offset:32
	ds_read_b128 v[232:235], v244 offset:0x3220
	s_setprio 2
	s_waitcnt lgkmcnt(2)
	v_mfma_f32_32x32x16_bf16 v[66:81], v[66:69], v[98:101], 0
	ds_read_b128 v[236:239], v244 offset:64
	v_mfma_f32_32x32x16_bf16 v[82:97], v[82:85], v[98:101], 0
	ds_read_b128 v[240:243], v244 offset:0x3240
	s_waitcnt lgkmcnt(2)
	v_mfma_f32_32x32x16_bf16 v[66:81], v[228:231], v[102:105], v[66:81]
	ds_read_b128 v[228:231], v244 offset:0x60
	v_mfma_f32_32x32x16_bf16 v[82:97], v[232:235], v[102:105], v[82:97]
	ds_read_b128 v[232:235], v244 offset:0x3260
	s_waitcnt lgkmcnt(2)
	v_mfma_f32_32x32x16_bf16 v[66:81], v[236:239], v[106:109], v[66:81]
	ds_read_b128 v[236:239], v244 offset:0x80
	v_mfma_f32_32x32x16_bf16 v[82:97], v[240:243], v[106:109], v[82:97]
	ds_read_b128 v[240:243], v244 offset:0x3280
	s_waitcnt lgkmcnt(2)
	v_mfma_f32_32x32x16_bf16 v[66:81], v[228:231], v[110:113], v[66:81]
	ds_read_b128 v[228:231], v244 offset:0xa0
	v_mfma_f32_32x32x16_bf16 v[82:97], v[232:235], v[110:113], v[82:97]
	ds_read_b128 v[232:235], v244 offset:0x32a0
	s_waitcnt lgkmcnt(2)
	v_mfma_f32_32x32x16_bf16 v[66:81], v[236:239], v[114:117], v[66:81]
	ds_read_b128 v[236:239], v244 offset:0xc0
	v_mfma_f32_32x32x16_bf16 v[82:97], v[240:243], v[114:117], v[82:97]
	ds_read_b128 v[240:243], v244 offset:0x32c0
	s_waitcnt lgkmcnt(2)
	v_mfma_f32_32x32x16_bf16 v[66:81], v[228:231], v[118:121], v[66:81]
	ds_read_b128 v[228:231], v244 offset:0xe0
	v_mfma_f32_32x32x16_bf16 v[82:97], v[232:235], v[118:121], v[82:97]
	ds_read_b128 v[232:235], v244 offset:0x32e0
	s_waitcnt lgkmcnt(2)
	v_mfma_f32_32x32x16_bf16 v[66:81], v[236:239], v[122:125], v[66:81]
	ds_read_b128 v[236:239], v244 offset:0x100
	v_mfma_f32_32x32x16_bf16 v[82:97], v[240:243], v[122:125], v[82:97]
	ds_read_b128 v[240:243], v244 offset:0x3300
	s_waitcnt lgkmcnt(2)
	v_mfma_f32_32x32x16_bf16 v[66:81], v[228:231], v[126:129], v[66:81]
	ds_read_b128 v[228:231], v244 offset:0x120
	v_mfma_f32_32x32x16_bf16 v[82:97], v[232:235], v[126:129], v[82:97]
	ds_read_b128 v[232:235], v244 offset:0x3320
	s_waitcnt lgkmcnt(2)
	v_mfma_f32_32x32x16_bf16 v[66:81], v[236:239], v[130:133], v[66:81]
	ds_read_b128 v[236:239], v244 offset:0x140
	v_mfma_f32_32x32x16_bf16 v[82:97], v[240:243], v[130:133], v[82:97]
	ds_read_b128 v[240:243], v244 offset:0x3340
	s_waitcnt lgkmcnt(2)
	v_mfma_f32_32x32x16_bf16 v[66:81], v[228:231], v[134:137], v[66:81]
	ds_read_b128 v[228:231], v244 offset:0x160
	v_mfma_f32_32x32x16_bf16 v[82:97], v[232:235], v[134:137], v[82:97]
	ds_read_b128 v[232:235], v244 offset:0x3360
	s_waitcnt lgkmcnt(2)
	v_mfma_f32_32x32x16_bf16 v[66:81], v[236:239], v[138:141], v[66:81]
	v_mfma_f32_32x32x16_bf16 v[82:97], v[240:243], v[138:141], v[82:97]
	s_waitcnt lgkmcnt(0)
	v_mfma_f32_32x32x16_bf16 v[66:81], v[228:231], v[142:145], v[66:81]
	v_mfma_f32_32x32x16_bf16 v[82:97], v[232:235], v[142:145], v[82:97]
	s_setprio 0
	s_nop 7
	s_nop 7
	v_cmp_neq_f32_e32 vcc, 0, v227
	s_cbranch_vccz .LBB0_823
	v_sub_f32 v66, v66, v227
	v_sub_f32 v82, v82, v227
	v_sub_f32 v67, v67, v227
	v_sub_f32 v83, v83, v227
	v_sub_f32 v68, v68, v227
	v_sub_f32 v84, v84, v227
	v_sub_f32 v69, v69, v227
	v_sub_f32 v85, v85, v227
	v_sub_f32 v70, v70, v227
	v_sub_f32 v86, v86, v227
	v_sub_f32 v71, v71, v227
	v_sub_f32 v87, v87, v227
	v_sub_f32 v72, v72, v227
	v_sub_f32 v88, v88, v227
	v_sub_f32 v73, v73, v227
	v_sub_f32 v89, v89, v227
	v_sub_f32 v74, v74, v227
	v_sub_f32 v90, v90, v227
	v_sub_f32 v75, v75, v227
	v_sub_f32 v91, v91, v227
	v_sub_f32 v76, v76, v227
	v_sub_f32 v92, v92, v227
	v_sub_f32 v77, v77, v227
	v_sub_f32 v93, v93, v227
	v_sub_f32 v78, v78, v227
	v_sub_f32 v94, v94, v227
	v_sub_f32 v79, v79, v227
	v_sub_f32 v95, v95, v227
	v_sub_f32 v80, v80, v227
	v_sub_f32 v96, v96, v227
	v_sub_f32 v81, v81, v227
	v_sub_f32 v97, v97, v227

; template <int DQK, int MODE, bool PIPE>
; DI void attn_core(const u16* __restrict__ Qg, const u16* __restrict__ Kg, const u16* __restrict__ Vtg, int ntiles,
;                   int kr_lo, int rs, int r_q, int c_q, int cs, const float* biasL, char* lds, f32x16 (&o)[4], float& l_out, int tid) {
;     ...
;   auto qk = [&](int t, f32x16& p0, f32x16& p1) {
;     const char* kb = lds + (t & 1) * A_BUF + r32 * KSTR + h * 16;
;     if (MODE != 0) {
; #pragma unroll
;       for (int i = 0; i < 16; ++i) { p0[i] = 0.f; p1[i] = 0.f; }
;     }
;     if (MODE == 0) {
;       constexpr int R = 4, NF = 2 * NKS;
;       const unsigned kaddr = (unsigned)(size_t)kb;
;       bf16x8 f[R];
;       SBAR();
;       f[0] = lds_rd128<0>(kaddr); f[1] = lds_rd128<32 * KSTR>(kaddr); f[2] = lds_rd128<32>(kaddr); f[3] = lds_rd128<32 * KSTR + 32>(kaddr);
;       SBAR();
;       __builtin_amdgcn_s_setprio(1);
;       QkStep<DQK, 0, NF, R>::run(kaddr, f, qf, p0, p1, negm);
;       __builtin_amdgcn_s_setprio(0);
;     ...
;     float tmx;
;     {
;       float u[11];
; #pragma unroll
;       for (int i = 0; i < 5; ++i) {
;         asm("v_max3_f32 %0, %1, %2, %3" : "=v"(u[2 * i]) : "v"(p0[3 * i]), "v"(p0[3 * i + 1]), "v"(p0[3 * i + 2]));
;         asm("v_max3_f32 %0, %1, %2, %3" : "=v"(u[2 * i + 1]) : "v"(p1[3 * i]), "v"(p1[3 * i + 1]), "v"(p1[3 * i + 2]));
;       }
;       asm("v_max3_f32 %0, %1, %2, %3" : "=v"(u[10]) : "v"(p0[15]), "v"(p1[15]), "v"(u[0]));
;       float w0, w1, w2, w3;
;       asm("v_max3_f32 %0, %1, %2, %3" : "=v"(w0) : "v"(u[1]), "v"(u[2]), "v"(u[3]));
;       asm("v_max3_f32 %0, %1, %2, %3" : "=v"(w1) : "v"(u[4]), "v"(u[5]), "v"(u[6]));
;       asm("v_max3_f32 %0, %1, %2, %3" : "=v"(w2) : "v"(u[7]), "v"(u[8]), "v"(u[9]));
;       asm("v_max3_f32 %0, %1, %2, %3" : "=v"(w3) : "v"(u[10]), "v"(w0), "v"(w1));
;       asm("v_max_f32 %0, %1, %2" : "=v"(tmx) : "v"(w2), "v"(w3));
;     }
;     const bool t0 = (t == 0);
;     if (__any(tmx > THR || (t0 && tmx < -THR))) {
;       tmx = fmaxf(tmx, __shfl_xor(tmx, 32));
;       const float delta = t0 ? tmx : fmaxf(tmx, 0.f);
;       const float alpha = __builtin_amdgcn_exp2f(-fmaxf(delta, 0.f));
;       m += delta; l *= alpha;
; #pragma unroll
;       for (int d = 0; d < 4; ++d)
; #pragma unroll
;         for (int i = 0; i < 16; ++i) o[d][i] *= alpha;
; #pragma unroll
;       for (int i = 0; i < 16; ++i) { p0[i] -= delta; p1[i] -= delta; }
.LBB0_842:
	s_bitcmp1_b32 s15, 0
	s_cselect_b32 s15, 0xa800, 0
	v_add3_u32 v177, s15, v167, v0
	ds_read_b128 v[98:101], v177 offset:0
	ds_read_b128 v[216:219], v177 offset:0x1200
	ds_read_b128 v[220:223], v177 offset:32
	ds_read_b128 v[224:227], v177 offset:0x1220
	s_setprio 2
	s_waitcnt lgkmcnt(2)
	v_mfma_f32_32x32x16_bf16 v[82:97], v[98:101], v[114:117], v[18:33]
	ds_read_b128 v[228:231], v177 offset:64
	v_mfma_f32_32x32x16_bf16 v[98:113], v[216:219], v[114:117], v[18:33]
	ds_read_b128 v[216:219], v177 offset:0x1240
	s_waitcnt lgkmcnt(2)
	v_mfma_f32_32x32x16_bf16 v[82:97], v[220:223], v[118:121], v[82:97]
	ds_read_b128 v[220:223], v177 offset:0x60
	v_mfma_f32_32x32x16_bf16 v[98:113], v[224:227], v[118:121], v[98:113]
	ds_read_b128 v[224:227], v177 offset:0x1260
	s_waitcnt lgkmcnt(2)
	v_mfma_f32_32x32x16_bf16 v[82:97], v[228:231], v[122:125], v[82:97]
	v_mfma_f32_32x32x16_bf16 v[98:113], v[216:219], v[122:125], v[98:113]
	s_waitcnt lgkmcnt(0)
	v_mfma_f32_32x32x16_bf16 v[82:97], v[220:223], v[126:129], v[82:97]
	v_mfma_f32_32x32x16_bf16 v[98:113], v[224:227], v[126:129], v[98:113]
	s_setprio 0
	v_max3_f32 v177, v82, v83, v84
	s_nop 7
	s_nop 7
	v_max3_f32 v199, v98, v99, v100
	v_max3_f32 v216, v85, v86, v87
	v_max3_f32 v217, v101, v102, v103
	v_max3_f32 v218, v88, v89, v90
	v_max3_f32 v177, v97, v113, v177
	v_max3_f32 v219, v104, v105, v106
	v_max3_f32 v220, v91, v92, v93
	v_max3_f32 v221, v107, v108, v109
	v_max3_f32 v199, v199, v216, v217
	v_max3_f32 v222, v94, v95, v96
	v_max3_f32 v223, v110, v111, v112
	v_max3_f32 v216, v218, v219, v220
	v_max3_f32 v217, v221, v222, v223
	v_max3_f32 v177, v177, v199, v216
	v_max_f32 v177, v217, v177
	v_cmp_lt_f32_e32 vcc, s66, v177
	s_cbranch_vccz .LBB0_844
	v_and_b32_e32 v19, 64, v189
	v_xor_b32_e32 v18, 32, v189
	v_add_u32_e32 v19, 64, v19
	v_cmp_lt_i32_e32 vcc, v18, v19
	s_nop 1
	v_cndmask_b32_e32 v18, v189, v18, vcc
	v_lshlrev_b32_e32 v18, 2, v18
	ds_bpermute_b32 v18, v18, v177
	s_waitcnt lgkmcnt(0)
	v_max3_f32 v18, v177, v18, 0
	v_exp_f32_e64 v20, -v18
	v_add_f32_e32 v175, v175, v18
	v_pk_add_f32 v[82:83], v[82:83], v[18:19] op_sel_hi:[1,0] neg_lo:[0,1] neg_hi:[0,1]
	v_pk_add_f32 v[98:99], v[98:99], v[18:19] op_sel_hi:[1,0] neg_lo:[0,1] neg_hi:[0,1]
	v_pk_add_f32 v[84:85], v[84:85], v[18:19] op_sel_hi:[1,0] neg_lo:[0,1] neg_hi:[0,1]
	v_pk_add_f32 v[100:101], v[100:101], v[18:19] op_sel_hi:[1,0] neg_lo:[0,1] neg_hi:[0,1]
	v_pk_add_f32 v[86:87], v[86:87], v[18:19] op_sel_hi:[1,0] neg_lo:[0,1] neg_hi:[0,1]
	v_pk_add_f32 v[102:103], v[102:103], v[18:19] op_sel_hi:[1,0] neg_lo:[0,1] neg_hi:[0,1]
	v_pk_add_f32 v[88:89], v[88:89], v[18:19] op_sel_hi:[1,0] neg_lo:[0,1] neg_hi:[0,1]
	v_pk_add_f32 v[104:105], v[104:105], v[18:19] op_sel_hi:[1,0] neg_lo:[0,1] neg_hi:[0,1]
	v_pk_add_f32 v[90:91], v[90:91], v[18:19] op_sel_hi:[1,0] neg_lo:[0,1] neg_hi:[0,1]
	v_pk_add_f32 v[106:107], v[106:107], v[18:19] op_sel_hi:[1,0] neg_lo:[0,1] neg_hi:[0,1]
	v_pk_add_f32 v[92:93], v[92:93], v[18:19] op_sel_hi:[1,0] neg_lo:[0,1] neg_hi:[0,1]
	v_pk_add_f32 v[108:109], v[108:109], v[18:19] op_sel_hi:[1,0] neg_lo:[0,1] neg_hi:[0,1]
	v_pk_add_f32 v[94:95], v[94:95], v[18:19] op_sel_hi:[1,0] neg_lo:[0,1] neg_hi:[0,1]
	v_pk_add_f32 v[110:111], v[110:111], v[18:19] op_sel_hi:[1,0] neg_lo:[0,1] neg_hi:[0,1]
	v_pk_add_f32 v[96:97], v[96:97], v[18:19] op_sel_hi:[1,0] neg_lo:[0,1] neg_hi:[0,1]
	v_pk_add_f32 v[112:113], v[112:113], v[18:19] op_sel_hi:[1,0] neg_lo:[0,1] neg_hi:[0,1]
	v_xor_b32_e32 v18, 0x80000000, v175
	v_mul_f32_e32 v176, v176, v20
	v_pk_mul_f32 v[80:81], v[80:81], v[20:21] op_sel_hi:[1,0]
	v_pk_mul_f32 v[78:79], v[78:79], v[20:21] op_sel_hi:[1,0]
	v_pk_mul_f32 v[76:77], v[76:77], v[20:21] op_sel_hi:[1,0]
	v_pk_mul_f32 v[74:75], v[74:75], v[20:21] op_sel_hi:[1,0]
	v_pk_mul_f32 v[72:73], v[72:73], v[20:21] op_sel_hi:[1,0]
	v_pk_mul_f32 v[70:71], v[70:71], v[20:21] op_sel_hi:[1,0]
	v_pk_mul_f32 v[68:69], v[68:69], v[20:21] op_sel_hi:[1,0]
	v_pk_mul_f32 v[66:67], v[66:67], v[20:21] op_sel_hi:[1,0]
	v_pk_mul_f32 v[64:65], v[64:65], v[20:21] op_sel_hi:[1,0]
	v_pk_mul_f32 v[62:63], v[62:63], v[20:21] op_sel_hi:[1,0]
	v_pk_mul_f32 v[60:61], v[60:61], v[20:21] op_sel_hi:[1,0]
	v_pk_mul_f32 v[58:59], v[58:59], v[20:21] op_sel_hi:[1,0]
	v_pk_mul_f32 v[56:57], v[56:57], v[20:21] op_sel_hi:[1,0]
	v_pk_mul_f32 v[54:55], v[54:55], v[20:21] op_sel_hi:[1,0]
	v_pk_mul_f32 v[52:53], v[52:53], v[20:21] op_sel_hi:[1,0]
	v_pk_mul_f32 v[50:51], v[50:51], v[20:21] op_sel_hi:[1,0]
	v_pk_mul_f32 v[48:49], v[48:49], v[20:21] op_sel_hi:[1,0]
	v_pk_mul_f32 v[46:47], v[46:47], v[20:21] op_sel_hi:[1,0]
	v_pk_mul_f32 v[44:45], v[44:45], v[20:21] op_sel_hi:[1,0]
	v_pk_mul_f32 v[42:43], v[42:43], v[20:21] op_sel_hi:[1,0]
	v_pk_mul_f32 v[40:41], v[40:41], v[20:21] op_sel_hi:[1,0]
	v_pk_mul_f32 v[38:39], v[38:39], v[20:21] op_sel_hi:[1,0]
	v_pk_mul_f32 v[36:37], v[36:37], v[20:21] op_sel_hi:[1,0]
	v_pk_mul_f32 v[34:35], v[34:35], v[20:21] op_sel_hi:[1,0]
	v_pk_mul_f32 v[16:17], v[16:17], v[20:21] op_sel_hi:[1,0]
	v_pk_mul_f32 v[14:15], v[14:15], v[20:21] op_sel_hi:[1,0]
	v_pk_mul_f32 v[12:13], v[12:13], v[20:21] op_sel_hi:[1,0]
	v_pk_mul_f32 v[10:11], v[10:11], v[20:21] op_sel_hi:[1,0]
	v_pk_mul_f32 v[8:9], v[8:9], v[20:21] op_sel_hi:[1,0]
	v_pk_mul_f32 v[6:7], v[6:7], v[20:21] op_sel_hi:[1,0]
	v_pk_mul_f32 v[4:5], v[4:5], v[20:21] op_sel_hi:[1,0]
	v_pk_mul_f32 v[2:3], v[2:3], v[20:21] op_sel_hi:[1,0]
	v_mov_b32_e32 v19, v18
	v_mov_b32_e32 v20, v18
	v_mov_b32_e32 v21, v18
	v_mov_b32_e32 v22, v18
	v_mov_b32_e32 v23, v18
	v_mov_b32_e32 v24, v18
	v_mov_b32_e32 v25, v18
	v_mov_b32_e32 v26, v18
	v_mov_b32_e32 v27, v18
	v_mov_b32_e32 v28, v18
	v_mov_b32_e32 v29, v18
	v_mov_b32_e32 v30, v18
	v_mov_b32_e32 v31, v18
	v_mov_b32_e32 v32, v18
	v_mov_b32_e32 v33, v18

; template <int DQK, int MODE, bool PIPE>
; DI void attn_core(const u16* __restrict__ Qg, const u16* __restrict__ Kg, const u16* __restrict__ Vtg, int ntiles,
;                   int kr_lo, int rs, int r_q, int c_q, int cs, const float* biasL, char* lds, f32x16 (&o)[4], float& l_out, int tid) {
;     ...
;   auto qk = [&](int t, f32x16& p0, f32x16& p1) {
;     const char* kb = lds + (t & 1) * A_BUF + r32 * KSTR + h * 16;
;     if (MODE != 0) {
; #pragma unroll
;       for (int i = 0; i < 16; ++i) { p0[i] = 0.f; p1[i] = 0.f; }
;     }
;     if (MODE == 0) {
;       constexpr int R = 4, NF = 2 * NKS;
;       const unsigned kaddr = (unsigned)(size_t)kb;
;       bf16x8 f[R];
;       SBAR();
;       f[0] = lds_rd128<0>(kaddr); f[1] = lds_rd128<32 * KSTR>(kaddr); f[2] = lds_rd128<32>(kaddr); f[3] = lds_rd128<32 * KSTR + 32>(kaddr);
;       SBAR();
;       __builtin_amdgcn_s_setprio(1);
;       QkStep<DQK, 0, NF, R>::run(kaddr, f, qf, p0, p1, negm);
;       __builtin_amdgcn_s_setprio(0);
;     ...
;     float tmx;
;     {
;       float u[11];
; #pragma unroll
;       for (int i = 0; i < 5; ++i) {
;         asm("v_max3_f32 %0, %1, %2, %3" : "=v"(u[2 * i]) : "v"(p0[3 * i]), "v"(p0[3 * i + 1]), "v"(p0[3 * i + 2]));
;         asm("v_max3_f32 %0, %1, %2, %3" : "=v"(u[2 * i + 1]) : "v"(p1[3 * i]), "v"(p1[3 * i + 1]), "v"(p1[3 * i + 2]));
;       }
;       asm("v_max3_f32 %0, %1, %2, %3" : "=v"(u[10]) : "v"(p0[15]), "v"(p1[15]), "v"(u[0]));
;       float w0, w1, w2, w3;
;       asm("v_max3_f32 %0, %1, %2, %3" : "=v"(w0) : "v"(u[1]), "v"(u[2]), "v"(u[3]));
;       asm("v_max3_f32 %0, %1, %2, %3" : "=v"(w1) : "v"(u[4]), "v"(u[5]), "v"(u[6]));
;       asm("v_max3_f32 %0, %1, %2, %3" : "=v"(w2) : "v"(u[7]), "v"(u[8]), "v"(u[9]));
;       asm("v_max3_f32 %0, %1, %2, %3" : "=v"(w3) : "v"(u[10]), "v"(w0), "v"(w1));
;       asm("v_max_f32 %0, %1, %2" : "=v"(tmx) : "v"(w2), "v"(w3));
;     }
;     const bool t0 = (t == 0);
;     if (__any(tmx > THR || (t0 && tmx < -THR))) {
;       tmx = fmaxf(tmx, __shfl_xor(tmx, 32));
;       const float delta = t0 ? tmx : fmaxf(tmx, 0.f);
;       const float alpha = __builtin_amdgcn_exp2f(-fmaxf(delta, 0.f));
;       m += delta; l *= alpha;
; #pragma unroll
;       for (int d = 0; d < 4; ++d)
; #pragma unroll
;         for (int i = 0; i < 16; ++i) o[d][i] *= alpha;
; #pragma unroll
;       for (int i = 0; i < 16; ++i) { p0[i] -= delta; p1[i] -= delta; }
.LBB0_858:
	s_bitcmp1_b32 s12, 0
	s_cselect_b32 s12, 0xa800, 0
	v_add3_u32 v160, s12, v167, v0
	ds_read_b128 v[98:101], v160 offset:0
	ds_read_b128 v[156:159], v160 offset:0x1200
	ds_read_b128 v[170:173], v160 offset:32
	ds_read_b128 v[174:177], v160 offset:0x1220
	s_setprio 2
	s_waitcnt lgkmcnt(2)
	v_mfma_f32_32x32x16_bf16 v[82:97], v[98:101], v[114:117], v[34:49]
	ds_read_b128 v[216:219], v160 offset:64
	v_mfma_f32_32x32x16_bf16 v[98:113], v[156:159], v[114:117], v[34:49]
	ds_read_b128 v[156:159], v160 offset:0x1240
	s_waitcnt lgkmcnt(2)
	v_mfma_f32_32x32x16_bf16 v[82:97], v[170:173], v[118:121], v[82:97]
	ds_read_b128 v[170:173], v160 offset:0x60
	v_mfma_f32_32x32x16_bf16 v[98:113], v[174:177], v[118:121], v[98:113]
	ds_read_b128 v[174:177], v160 offset:0x1260
	s_waitcnt lgkmcnt(2)
	v_mfma_f32_32x32x16_bf16 v[82:97], v[216:219], v[122:125], v[82:97]
	v_mfma_f32_32x32x16_bf16 v[98:113], v[156:159], v[122:125], v[98:113]
	s_waitcnt lgkmcnt(0)
	v_mfma_f32_32x32x16_bf16 v[82:97], v[170:173], v[126:129], v[82:97]
	v_mfma_f32_32x32x16_bf16 v[98:113], v[174:177], v[126:129], v[98:113]
	s_setprio 0
	v_max3_f32 v156, v82, v83, v84
	s_nop 7
	s_nop 7
	v_max3_f32 v157, v98, v99, v100
	v_max3_f32 v158, v85, v86, v87
	v_max3_f32 v159, v101, v102, v103
	v_max3_f32 v160, v88, v89, v90
	v_max3_f32 v156, v97, v113, v156
	v_max3_f32 v161, v104, v105, v106
	v_max3_f32 v163, v91, v92, v93
	v_max3_f32 v169, v107, v108, v109
	v_max3_f32 v157, v157, v158, v159
	v_max3_f32 v170, v94, v95, v96
	v_max3_f32 v171, v110, v111, v112
	v_max3_f32 v158, v160, v161, v163
	v_max3_f32 v159, v169, v170, v171
	v_max3_f32 v156, v156, v157, v158
	v_max_f32 v156, v159, v156
	v_cmp_lt_f32_e32 vcc, s66, v156
	s_cbranch_vccz .LBB0_860
	ds_bpermute_b32 v34, v162, v156
	s_waitcnt lgkmcnt(0)
	v_max3_f32 v34, v156, v34, 0
	v_exp_f32_e64 v36, -v34
	v_add_f32_e32 v154, v154, v34
	v_pk_add_f32 v[82:83], v[82:83], v[34:35] op_sel_hi:[1,0] neg_lo:[0,1] neg_hi:[0,1]
	v_pk_add_f32 v[98:99], v[98:99], v[34:35] op_sel_hi:[1,0] neg_lo:[0,1] neg_hi:[0,1]
	v_pk_add_f32 v[84:85], v[84:85], v[34:35] op_sel_hi:[1,0] neg_lo:[0,1] neg_hi:[0,1]
	v_pk_add_f32 v[100:101], v[100:101], v[34:35] op_sel_hi:[1,0] neg_lo:[0,1] neg_hi:[0,1]
	v_pk_add_f32 v[86:87], v[86:87], v[34:35] op_sel_hi:[1,0] neg_lo:[0,1] neg_hi:[0,1]
	v_pk_add_f32 v[102:103], v[102:103], v[34:35] op_sel_hi:[1,0] neg_lo:[0,1] neg_hi:[0,1]
	v_pk_add_f32 v[88:89], v[88:89], v[34:35] op_sel_hi:[1,0] neg_lo:[0,1] neg_hi:[0,1]
	v_pk_add_f32 v[104:105], v[104:105], v[34:35] op_sel_hi:[1,0] neg_lo:[0,1] neg_hi:[0,1]
	v_pk_add_f32 v[90:91], v[90:91], v[34:35] op_sel_hi:[1,0] neg_lo:[0,1] neg_hi:[0,1]
	v_pk_add_f32 v[106:107], v[106:107], v[34:35] op_sel_hi:[1,0] neg_lo:[0,1] neg_hi:[0,1]
	v_pk_add_f32 v[92:93], v[92:93], v[34:35] op_sel_hi:[1,0] neg_lo:[0,1] neg_hi:[0,1]
	v_pk_add_f32 v[108:109], v[108:109], v[34:35] op_sel_hi:[1,0] neg_lo:[0,1] neg_hi:[0,1]
	v_pk_add_f32 v[94:95], v[94:95], v[34:35] op_sel_hi:[1,0] neg_lo:[0,1] neg_hi:[0,1]
	v_pk_add_f32 v[110:111], v[110:111], v[34:35] op_sel_hi:[1,0] neg_lo:[0,1] neg_hi:[0,1]
	v_pk_add_f32 v[96:97], v[96:97], v[34:35] op_sel_hi:[1,0] neg_lo:[0,1] neg_hi:[0,1]
	v_pk_add_f32 v[112:113], v[112:113], v[34:35] op_sel_hi:[1,0] neg_lo:[0,1] neg_hi:[0,1]
	v_xor_b32_e32 v34, 0x80000000, v154
	v_mul_f32_e32 v155, v155, v36
	v_pk_mul_f32 v[80:81], v[80:81], v[36:37] op_sel_hi:[1,0]
	v_pk_mul_f32 v[78:79], v[78:79], v[36:37] op_sel_hi:[1,0]
	v_pk_mul_f32 v[76:77], v[76:77], v[36:37] op_sel_hi:[1,0]
	v_pk_mul_f32 v[74:75], v[74:75], v[36:37] op_sel_hi:[1,0]
	v_pk_mul_f32 v[72:73], v[72:73], v[36:37] op_sel_hi:[1,0]
	v_pk_mul_f32 v[70:71], v[70:71], v[36:37] op_sel_hi:[1,0]
	v_pk_mul_f32 v[68:69], v[68:69], v[36:37] op_sel_hi:[1,0]
	v_pk_mul_f32 v[66:67], v[66:67], v[36:37] op_sel_hi:[1,0]
	v_pk_mul_f32 v[64:65], v[64:65], v[36:37] op_sel_hi:[1,0]
	v_pk_mul_f32 v[62:63], v[62:63], v[36:37] op_sel_hi:[1,0]
	v_pk_mul_f32 v[60:61], v[60:61], v[36:37] op_sel_hi:[1,0]
	v_pk_mul_f32 v[58:59], v[58:59], v[36:37] op_sel_hi:[1,0]
	v_pk_mul_f32 v[56:57], v[56:57], v[36:37] op_sel_hi:[1,0]
	v_pk_mul_f32 v[54:55], v[54:55], v[36:37] op_sel_hi:[1,0]
	v_pk_mul_f32 v[52:53], v[52:53], v[36:37] op_sel_hi:[1,0]
	v_pk_mul_f32 v[50:51], v[50:51], v[36:37] op_sel_hi:[1,0]
	v_pk_mul_f32 v[32:33], v[32:33], v[36:37] op_sel_hi:[1,0]
	v_pk_mul_f32 v[30:31], v[30:31], v[36:37] op_sel_hi:[1,0]
	v_pk_mul_f32 v[28:29], v[28:29], v[36:37] op_sel_hi:[1,0]
	v_pk_mul_f32 v[26:27], v[26:27], v[36:37] op_sel_hi:[1,0]
	v_pk_mul_f32 v[24:25], v[24:25], v[36:37] op_sel_hi:[1,0]
	v_pk_mul_f32 v[22:23], v[22:23], v[36:37] op_sel_hi:[1,0]
	v_pk_mul_f32 v[20:21], v[20:21], v[36:37] op_sel_hi:[1,0]
	v_pk_mul_f32 v[18:19], v[18:19], v[36:37] op_sel_hi:[1,0]
	v_pk_mul_f32 v[16:17], v[16:17], v[36:37] op_sel_hi:[1,0]
	v_pk_mul_f32 v[14:15], v[14:15], v[36:37] op_sel_hi:[1,0]
	v_pk_mul_f32 v[12:13], v[12:13], v[36:37] op_sel_hi:[1,0]
	v_pk_mul_f32 v[10:11], v[10:11], v[36:37] op_sel_hi:[1,0]
	v_pk_mul_f32 v[8:9], v[8:9], v[36:37] op_sel_hi:[1,0]
	v_pk_mul_f32 v[6:7], v[6:7], v[36:37] op_sel_hi:[1,0]
	v_pk_mul_f32 v[4:5], v[4:5], v[36:37] op_sel_hi:[1,0]
	v_pk_mul_f32 v[2:3], v[2:3], v[36:37] op_sel_hi:[1,0]
	v_mov_b32_e32 v35, v34
	v_mov_b32_e32 v36, v34
	v_mov_b32_e32 v37, v34
	v_mov_b32_e32 v38, v34
	v_mov_b32_e32 v39, v34
	v_mov_b32_e32 v40, v34
	v_mov_b32_e32 v41, v34
	v_mov_b32_e32 v42, v34
	v_mov_b32_e32 v43, v34
	v_mov_b32_e32 v44, v34
	v_mov_b32_e32 v45, v34
	v_mov_b32_e32 v46, v34
	v_mov_b32_e32 v47, v34
	v_mov_b32_e32 v48, v34
	v_mov_b32_e32 v49, v34
